# v9: + leader releases XCD before its own L1 invalidate in the grid barrier; GQA QK^T K-fragment LDS prefetch deepened (8 in flight) using free VGPRs
# baseline (speedup 1.0000x reference)
; __device__ __forceinline__ unsigned xb_add(unsigned* p, unsigned v) { return __hip_atomic_fetch_add(p, v, __ATOMIC_RELAXED, __HIP_MEMORY_SCOPE_AGENT); }
; __device__ __forceinline__ void xcd_barrier(const XcdBarrier& b) {
;     ...
;             __builtin_amdgcn_fence(__ATOMIC_ACQUIRE, "agent");
;             xb_add(&bar[XB_XGEN(b.x)], 1u);
;             asm volatile("s_waitcnt vmcnt(0)" ::: "memory");
.LBB0_187:
	s_or_b64 exec, exec, s[0:1]
	s_mov_b64 s[0:1], exec
	v_mbcnt_lo_u32_b32 v0, s0, 0
	v_mbcnt_hi_u32_b32 v0, s1, v0
	v_cmp_eq_u32_e32 vcc, 0, v0
	s_waitcnt vmcnt(0)
	s_and_saveexec_b64 s[6:7], vcc
	s_cbranch_execz .LBB0_189
	s_bcnt1_i32_b64 s0, s[0:1]
	v_mov_b32_e32 v0, 0x2000
	v_mov_b32_e32 v1, s0
	global_atomic_add v0, v1, s[4:5] offset:1024
.LBB0_189:
	s_or_b64 exec, exec, s[6:7]
	buffer_inv sc1
	s_waitcnt vmcnt(0)

; __device__ __forceinline__ unsigned xb_add(unsigned* p, unsigned v) { return __hip_atomic_fetch_add(p, v, __ATOMIC_RELAXED, __HIP_MEMORY_SCOPE_AGENT); }
; __device__ __forceinline__ void xcd_barrier(const XcdBarrier& b) {
;     ...
;             __builtin_amdgcn_fence(__ATOMIC_ACQUIRE, "agent");
;             xb_add(&bar[XB_XGEN(b.x)], 1u);
;             asm volatile("s_waitcnt vmcnt(0)" ::: "memory");
.LBB0_432:
	s_or_b64 exec, exec, s[0:1]
	s_mov_b64 s[0:1], exec
	v_mbcnt_lo_u32_b32 v0, s0, 0
	v_mbcnt_hi_u32_b32 v0, s1, v0
	v_cmp_eq_u32_e32 vcc, 0, v0
	s_waitcnt vmcnt(0)
	s_and_saveexec_b64 s[8:9], vcc
	s_cbranch_execz .LBB0_434
	s_bcnt1_i32_b64 s0, s[0:1]
	v_mov_b32_e32 v0, 0x2000
	v_mov_b32_e32 v1, s0
	global_atomic_add v0, v1, s[4:5] offset:1024
.LBB0_434:
	s_or_b64 exec, exec, s[8:9]
	buffer_inv sc1
	s_waitcnt vmcnt(0)

; __device__ __forceinline__ unsigned xb_add(unsigned* p, unsigned v) { return __hip_atomic_fetch_add(p, v, __ATOMIC_RELAXED, __HIP_MEMORY_SCOPE_AGENT); }
; __device__ __forceinline__ void xcd_barrier(const XcdBarrier& b) {
;     ...
;             __builtin_amdgcn_fence(__ATOMIC_ACQUIRE, "agent");
;             xb_add(&bar[XB_XGEN(b.x)], 1u);
;             asm volatile("s_waitcnt vmcnt(0)" ::: "memory");
.LBB0_591:
	s_or_b64 exec, exec, s[0:1]
	s_mov_b64 s[0:1], exec
	v_mbcnt_lo_u32_b32 v0, s0, 0
	v_mbcnt_hi_u32_b32 v0, s1, v0
	v_cmp_eq_u32_e32 vcc, 0, v0
	s_waitcnt vmcnt(0)
	s_and_saveexec_b64 s[10:11], vcc
	s_cbranch_execz .LBB0_593
	s_bcnt1_i32_b64 s0, s[0:1]
	v_mov_b32_e32 v0, 0x2000
	v_mov_b32_e32 v1, s0
	global_atomic_add v0, v1, s[8:9] offset:1024
.LBB0_593:
	s_or_b64 exec, exec, s[10:11]
	buffer_inv sc1
	s_waitcnt vmcnt(0)

; __device__ __forceinline__ void finishSM(f32x16& p0, f32x16& p1, float alpha, float& l_reg, bf16x8& pa0, bf16x8& pa1, bf16x8& pa2, bf16x8& pa3) {
;     ...
;   for (int r = 0; r < 16; ++r) p1[r] = __builtin_amdgcn_exp2f(p1[r]);
;   float ps = 0;
; #pragma unroll
;   for (int r = 0; r < 16; ++r) ps += p0[r];
; #pragma unroll
;   for (int r = 0; r < 16; ++r) ps += p1[r];
;   { auto rr = __builtin_amdgcn_permlane32_swap(__float_as_uint(ps), __float_as_uint(ps), false, false);
;     ps = __uint_as_float(rr[0]) + __uint_as_float(rr[1]); }
;   l_reg = l_reg * alpha + ps;
;     ...
;   PK4(p0, 0, pa0); PK4(p0, 8, pa1); PK4(p1, 0, pa2); PK4(p1, 8, pa3);
; template <int DKR, int NQ>
; __device__ __forceinline__ void qkt(f32x16& p0, f32x16& p1, const char* Ks, const char* Krs, const char* Qrs, const bf16x8* qr, int r32, int hi, int lane) {
;   p0 = f32x16{}; p1 = f32x16{};
; #pragma unroll
;   for (int d0 = 0; d0 < 8; ++d0) { int cb = (d0 * 16 + hi * 8) * 2;
;     bf16x8 b0 = *reinterpret_cast<const bf16x8*>(Ks + KSWZ(r32, cb));
;     bf16x8 b1 = *reinterpret_cast<const bf16x8*>(Ks + KSWZ(32 + r32, cb));
;     bf16x8 qf;
;     if (d0 >= 8 - NQ) qf = *reinterpret_cast<const bf16x8*>(Qrs + (d0 - (8 - NQ) + 4) * 1024 + lane * 16); else qf = qr[d0];
;     p0 = __builtin_amdgcn_mfma_f32_32x32x16_bf16(b0, qf, p0, 0, 0, 0);
;     p1 = __builtin_amdgcn_mfma_f32_32x32x16_bf16(b1, qf, p1, 0, 0, 0); }
.LBB0_616:
	ds_read_b128 v[64:67], v194 offset:49152
	ds_read_b128 v[68:71], v194 offset:57344
	ds_read_b128 v[204:207], v200 offset:49152
	ds_read_b128 v[208:211], v200 offset:57344
	ds_read_b128 v[232:235], v201 offset:49152
	ds_read_b128 v[236:239], v201 offset:57344
	ds_read_b128 v[248:251], v195 offset:49152
	ds_read_b128 v[252:255], v195 offset:57344
	v_exp_f32_e32 v156, v156
	v_exp_f32_e32 v157, v157
	s_waitcnt lgkmcnt(7)
	v_mfma_f32_32x32x16_bf16 v[80:95], v[64:67], v[124:127], 0
	v_exp_f32_e32 v154, v154
	v_exp_f32_e32 v155, v155
	v_exp_f32_e32 v148, v148
	v_exp_f32_e32 v149, v149
	v_exp_f32_e32 v146, v146
	v_exp_f32_e32 v147, v147
	v_exp_f32_e32 v144, v144
	s_waitcnt lgkmcnt(6)
	v_mfma_f32_32x32x16_bf16 v[64:79], v[68:71], v[124:127], 0
	v_exp_f32_e32 v145, v145
	v_exp_f32_e32 v158, v158
	v_exp_f32_e32 v159, v159
	v_exp_f32_e32 v152, v152
	v_exp_f32_e32 v153, v153
	v_exp_f32_e32 v150, v150
	v_exp_f32_e32 v151, v151
	s_waitcnt lgkmcnt(5)
	v_mfma_f32_32x32x16_bf16 v[80:95], v[204:207], v[120:123], v[80:95]
	ds_read_b128 v[204:207], v196 offset:49152
	s_waitcnt lgkmcnt(5)
	v_mfma_f32_32x32x16_bf16 v[64:79], v[208:211], v[120:123], v[64:79]
	ds_read_b128 v[208:211], v196 offset:57344
	s_waitcnt lgkmcnt(5)
	v_mfma_f32_32x32x16_bf16 v[80:95], v[232:235], v[116:119], v[80:95]
	ds_read_b128 v[232:235], v197 offset:49152
	s_waitcnt lgkmcnt(5)
	v_mfma_f32_32x32x16_bf16 v[64:79], v[236:239], v[116:119], v[64:79]
	ds_read_b128 v[236:239], v197 offset:57344
	s_waitcnt lgkmcnt(5)
	v_mfma_f32_32x32x16_bf16 v[80:95], v[248:251], v[112:115], v[80:95]
	ds_read_b128 v[248:251], v198 offset:49152
	s_waitcnt lgkmcnt(5)
	v_mfma_f32_32x32x16_bf16 v[64:79], v[252:255], v[112:115], v[64:79]
	ds_read_b128 v[252:255], v198 offset:57344
	s_waitcnt lgkmcnt(5)
	v_mfma_f32_32x32x16_bf16 v[80:95], v[204:207], v[108:111], v[80:95]
	ds_read_b128 v[204:207], v199 offset:49152
	s_waitcnt lgkmcnt(5)
	v_mfma_f32_32x32x16_bf16 v[64:79], v[208:211], v[108:111], v[64:79]
	ds_read_b128 v[208:211], v199 offset:57344
	s_waitcnt lgkmcnt(5)
	v_mfma_f32_32x32x16_bf16 v[80:95], v[232:235], v[104:107], v[80:95]
	s_waitcnt lgkmcnt(4)
	v_mfma_f32_32x32x16_bf16 v[64:79], v[236:239], v[104:107], v[64:79]
	s_waitcnt lgkmcnt(3)
	v_mfma_f32_32x32x16_bf16 v[80:95], v[248:251], v[100:103], v[80:95]
	s_waitcnt lgkmcnt(2)
	v_mfma_f32_32x32x16_bf16 v[64:79], v[252:255], v[100:103], v[64:79]
	s_waitcnt lgkmcnt(1)
	v_mfma_f32_32x32x16_bf16 v[80:95], v[204:207], v[96:99], v[80:95]
	v_add_f32_e32 v204, 0, v160
	v_add_f32_e32 v204, v175, v204
	v_add_f32_e32 v204, v161, v204
	v_add_f32_e32 v204, v174, v204
	v_add_f32_e32 v204, v162, v204
	v_add_f32_e32 v204, v173, v204
	v_add_f32_e32 v204, v163, v204
	v_add_f32_e32 v204, v172, v204
	v_add_f32_e32 v204, v164, v204
	v_add_f32_e32 v204, v171, v204
	v_add_f32_e32 v204, v165, v204
	v_add_f32_e32 v204, v170, v204
	v_add_f32_e32 v204, v166, v204
	v_add_f32_e32 v204, v169, v204
	v_add_f32_e32 v204, v167, v204
	v_add_f32_e32 v204, v168, v204
	v_add_f32_e32 v204, v156, v204
	v_add_f32_e32 v204, v157, v204
	v_add_f32_e32 v204, v154, v204
	v_add_f32_e32 v204, v155, v204
	v_add_f32_e32 v204, v148, v204
	v_add_f32_e32 v204, v149, v204
	v_add_f32_e32 v204, v146, v204
	v_add_f32_e32 v204, v147, v204
	v_add_f32_e32 v204, v144, v204
	v_add_f32_e32 v204, v145, v204
	s_waitcnt lgkmcnt(0)
	v_mfma_f32_32x32x16_bf16 v[64:79], v[208:211], v[96:99], v[64:79]
	v_add_f32_e32 v204, v158, v204
	v_add_f32_e32 v204, v159, v204
	v_add_f32_e32 v204, v152, v204
	v_add_f32_e32 v204, v153, v204
	v_add_f32_e32 v204, v150, v204
	v_add_f32_e32 v205, v151, v204
	v_mov_b32_e32 v206, v205
	s_nop 1
	v_permlane32_swap_b32_e32 v205, v206
	v_cvt_pk_bf16_f32 v160, v160, v175
	v_cvt_pk_bf16_f32 v161, v161, v174
	v_cvt_pk_bf16_f32 v162, v162, v173
	v_cvt_pk_bf16_f32 v163, v163, v172
	v_cvt_pk_bf16_f32 v164, v164, v171
	v_cvt_pk_bf16_f32 v165, v165, v170
	v_cvt_pk_bf16_f32 v166, v166, v169
	v_cvt_pk_bf16_f32 v167, v167, v168
	v_cvt_pk_bf16_f32 v168, v156, v157
	v_cvt_pk_bf16_f32 v169, v154, v155
	v_cvt_pk_bf16_f32 v170, v148, v149
	v_cvt_pk_bf16_f32 v171, v146, v147
	v_cvt_pk_bf16_f32 v172, v144, v145
	v_cvt_pk_bf16_f32 v173, v158, v159
	v_cvt_pk_bf16_f32 v174, v152, v153
	v_cvt_pk_bf16_f32 v175, v150, v151
	s_nop 0
	v_permlane32_swap_b32_e32 v160, v162
	v_permlane32_swap_b32_e32 v161, v163
	v_permlane32_swap_b32_e32 v164, v166
	v_permlane32_swap_b32_e32 v165, v167
	v_permlane32_swap_b32_e32 v168, v170
	v_permlane32_swap_b32_e32 v169, v171
	v_permlane32_swap_b32_e32 v172, v174
	v_permlane32_swap_b32_e32 v173, v175
	s_mov_b32 s0, 0xffff4000
	v_add_co_u32_e32 v144, vcc, s0, v180
	s_movk_i32 s0, 0x8000
	s_nop 0
	v_addc_co_u32_e32 v145, vcc, -1, v181, vcc
	v_add_co_u32_e32 v148, vcc, s0, v180
	s_mov_b32 s0, 0xff6f4000
	s_nop 0
	v_addc_co_u32_e32 v149, vcc, -1, v181, vcc
	v_add_co_u32_e32 v152, vcc, s0, v180
	s_mov_b32 s0, 0xff6f8000
	s_nop 0
	v_addc_co_u32_e32 v153, vcc, -1, v181, vcc
	v_add_co_u32_e32 v156, vcc, s0, v180
	global_load_dwordx4 v[144:147], v[144:145], off
	s_nop 0
	global_load_dwordx4 v[148:151], v[148:149], off
	v_addc_co_u32_e32 v157, vcc, -1, v181, vcc
	global_load_dwordx4 v[152:155], v[152:153], off
	s_nop 0
	global_load_dwordx4 v[156:159], v[156:157], off
	ds_read_b64_tr_b16 v[208:209], v188 offset:0
	ds_read_b64_tr_b16 v[210:211], v188 offset:0x800
	ds_read_b64_tr_b16 v[214:215], v188 offset:0x1000
	ds_read_b64_tr_b16 v[216:217], v188 offset:0x1800
	ds_read_b64_tr_b16 v[218:219], v188 offset:0x2000
	ds_read_b64_tr_b16 v[220:221], v188 offset:0x2800
	ds_read_b64_tr_b16 v[222:223], v188 offset:0x3000
	ds_read_b64_tr_b16 v[224:225], v188 offset:0x3800
	s_waitcnt lgkmcnt(0)
; __device__ __forceinline__ void pv_sm(f32x16* o, int vb, bf16x8 pa0, bf16x8 pa1, bf16x8 pa2, bf16x8 pa3, f32x16& p0, f32x16& p1, float& m_reg, float& mn, float& alpha, const float SCALE) {
;   const float C = SCALE * 1.4426950408889634f;
;   pv_one<0>(o[0], vb, pa0, pa1, pa2, pa3);
;   float pmax = p0[0];
; #pragma unroll
;   for (int r = 1; r < 16; ++r) pmax = fmaxf(pmax, p0[r]);
;   pv_one<1>(o[1], vb, pa0, pa1, pa2, pa3);
; #pragma unroll
;   for (int r = 0; r < 16; ++r) pmax = fmaxf(pmax, p1[r]);
;   { auto rr = __builtin_amdgcn_permlane32_swap(__float_as_uint(pmax), __float_as_uint(pmax), false, false);
;     pmax = fmaxf(__uint_as_float(rr[0]), __uint_as_float(rr[1])); }
;   if (__builtin_expect(__all(pmax - m_reg <= THR / SCALE), 1)) { mn = m_reg; alpha = 1.f; }
;   else { mn = fmaxf(m_reg, pmax); alpha = __builtin_amdgcn_exp2f((m_reg - mn) * C); m_reg = mn; }
;   const float mnC = -mn * C;
;   pv_one<2>(o[2], vb, pa0, pa1, pa2, pa3);
; #pragma unroll
;   for (int r = 0; r < 16; ++r) p0[r] = fmaf(p0[r], C, mnC);
; #pragma unroll
;   for (int r = 0; r < 16; ++r) p1[r] = fmaf(p1[r], C, mnC);
;   pv_one<3>(o[3], vb, pa0, pa1, pa2, pa3);
; #pragma unroll
;   for (int r = 0; r < 16; ++r) p0[r] = __builtin_amdgcn_exp2f(p0[r]);
; }
	s_nop 0
	v_mfma_f32_32x32x16_bf16 v[0:15], v[160:163], v[208:211], v[0:15]
	ds_read_b64_tr_b16 v[208:209], v188 offset:0x200
	ds_read_b64_tr_b16 v[210:211], v188 offset:0xa00
	v_max_f32_e32 v204, v81, v81
	v_max_f32_e32 v207, v80, v80
	v_max_f32_e32 v204, v207, v204
	v_max3_f32 v204, v204, v82, v83
	v_max3_f32 v204, v204, v84, v85
	v_mfma_f32_32x32x16_bf16 v[0:15], v[164:167], v[214:217], v[0:15]
	ds_read_b64_tr_b16 v[214:215], v188 offset:0x1200
	ds_read_b64_tr_b16 v[216:217], v188 offset:0x1a00
	v_max3_f32 v204, v204, v86, v87
	v_max3_f32 v204, v204, v88, v89
	v_max3_f32 v204, v204, v90, v91
	v_max3_f32 v204, v204, v92, v93
	v_max3_f32 v204, v204, v94, v95
	v_mfma_f32_32x32x16_bf16 v[0:15], v[168:171], v[218:221], v[0:15]
	ds_read_b64_tr_b16 v[218:219], v188 offset:0x2200
	ds_read_b64_tr_b16 v[220:221], v188 offset:0x2a00
	ds_read_b64_tr_b16 v[226:227], v188 offset:0x3200
	ds_read_b64_tr_b16 v[228:229], v188 offset:0x3a00
	s_waitcnt lgkmcnt(0)
	v_mfma_f32_32x32x16_bf16 v[0:15], v[172:175], v[222:225], v[0:15]
	v_mfma_f32_32x32x16_bf16 v[48:63], v[160:163], v[208:211], v[48:63]
	v_max3_f32 v204, v204, v64, v65
	v_max3_f32 v204, v204, v66, v67
	v_max3_f32 v204, v204, v68, v69
	v_max3_f32 v204, v204, v70, v71
	v_max3_f32 v204, v204, v72, v73
	v_max3_f32 v204, v204, v74, v75
	v_max3_f32 v204, v204, v76, v77
	v_mfma_f32_32x32x16_bf16 v[48:63], v[164:167], v[214:217], v[48:63]
	v_max3_f32 v204, v204, v78, v79
	v_mov_b32_e32 v207, v204
	s_nop 1
	v_permlane32_swap_b32_e32 v204, v207
	v_max_f32_e32 v207, v207, v207
	v_max_f32_e32 v204, v204, v204
	v_max_f32_e32 v204, v204, v207
	v_max_f32_e32 v208, v203, v203
	v_sub_f32_e32 v207, v204, v203
	v_max_f32_e32 v204, v208, v204
	v_sub_f32_e32 v208, v203, v204
	v_mul_f32_e32 v208, 0x3e0293ee, v208
	v_mfma_f32_32x32x16_bf16 v[48:63], v[168:171], v[218:221], v[48:63]
	v_exp_f32_e32 v208, v208
	v_cmp_ge_f32_e32 vcc, s47, v207
	s_cmp_eq_u64 vcc, exec
	s_cselect_b64 s[4:5], -1, 0
	v_cndmask_b32_e64 v207, v208, 1.0, s[4:5]
	ds_read_b64_tr_b16 v[208:209], v188 offset:0x400
	ds_read_b64_tr_b16 v[210:211], v188 offset:0xc00
	ds_read_b64_tr_b16 v[214:215], v188 offset:0x1400
	v_mfma_f32_32x32x16_bf16 v[48:63], v[172:175], v[226:229], v[48:63]
	ds_read_b64_tr_b16 v[216:217], v188 offset:0x1c00
	ds_read_b64_tr_b16 v[218:219], v188 offset:0x2400
	ds_read_b64_tr_b16 v[220:221], v188 offset:0x2c00
	ds_read_b64_tr_b16 v[222:223], v188 offset:0x3400
	ds_read_b64_tr_b16 v[224:225], v188 offset:0x3c00
	s_waitcnt lgkmcnt(0)
	v_mfma_f32_32x32x16_bf16 v[32:47], v[160:163], v[208:211], v[32:47]
	ds_read_b64_tr_b16 v[208:209], v188 offset:0x600
	ds_read_b64_tr_b16 v[210:211], v188 offset:0xe00
	v_mfma_f32_32x32x16_bf16 v[32:47], v[164:167], v[214:217], v[32:47]
	ds_read_b64_tr_b16 v[214:215], v188 offset:0x1600
	ds_read_b64_tr_b16 v[216:217], v188 offset:0x1e00
	v_mfma_f32_32x32x16_bf16 v[32:47], v[168:171], v[218:221], v[32:47]
	ds_read_b64_tr_b16 v[218:219], v188 offset:0x2600
	ds_read_b64_tr_b16 v[220:221], v188 offset:0x2e00
	ds_read_b64_tr_b16 v[226:227], v188 offset:0x3600
	ds_read_b64_tr_b16 v[228:229], v188 offset:0x3e00
	s_waitcnt lgkmcnt(0)
	v_mfma_f32_32x32x16_bf16 v[32:47], v[172:175], v[222:225], v[32:47]
	v_mfma_f32_32x32x16_bf16 v[16:31], v[160:163], v[208:211], v[16:31]
	s_barrier
	s_waitcnt vmcnt(4)
	v_cmp_gt_f32_e32 vcc, 1.0, v207
	s_waitcnt vmcnt(4)
	ds_write_b128 v192, v[132:135]
	ds_write_b128 v193, v[140:143]
	ds_write_b128 v190, v[128:131] offset:32768
	ds_write_b128 v191, v[136:139] offset:32768
	v_mfma_f32_32x32x16_bf16 v[16:31], v[164:167], v[214:217], v[16:31]
	v_mfma_f32_32x32x16_bf16 v[16:31], v[168:171], v[218:221], v[16:31]
	v_mfma_f32_32x32x16_bf16 v[16:31], v[172:175], v[226:229], v[16:31]
	s_cbranch_vccz .LBB0_620
	s_and_saveexec_b64 s[0:1], s[2:3]
	ds_write_b32 v185, v207 offset:128
	s_or_b64 exec, exec, s[0:1]
	s_waitcnt lgkmcnt(0)
	v_add_u32_e32 v172, v179, v176
	ds_read_b128 v[160:163], v172 offset:224
	ds_read_b128 v[164:167], v172 offset:192
	ds_read_b128 v[168:171], v172 offset:160
	ds_read_b128 v[172:175], v172 offset:128
	s_waitcnt lgkmcnt(3)
	v_pk_mul_f32 v[12:13], v[12:13], v[160:161]
	s_waitcnt lgkmcnt(2)
	v_pk_mul_f32 v[8:9], v[8:9], v[164:165]
	s_waitcnt lgkmcnt(1)
	v_pk_mul_f32 v[4:5], v[4:5], v[168:169]
	v_pk_mul_f32 v[14:15], v[14:15], v[162:163]
	v_pk_mul_f32 v[10:11], v[10:11], v[166:167]
	v_pk_mul_f32 v[6:7], v[6:7], v[170:171]
	s_waitcnt lgkmcnt(0)
	v_pk_mul_f32 v[2:3], v[2:3], v[174:175]
	v_pk_mul_f32 v[0:1], v[0:1], v[172:173]
	v_pk_mul_f32 v[60:61], v[60:61], v[160:161]
	v_pk_mul_f32 v[56:57], v[56:57], v[164:165]
	v_pk_mul_f32 v[52:53], v[52:53], v[168:169]
	v_pk_mul_f32 v[62:63], v[62:63], v[162:163]
	v_pk_mul_f32 v[58:59], v[58:59], v[166:167]
	v_pk_mul_f32 v[54:55], v[54:55], v[170:171]
	v_pk_mul_f32 v[50:51], v[50:51], v[174:175]
	v_pk_mul_f32 v[48:49], v[48:49], v[172:173]
	v_pk_mul_f32 v[44:45], v[44:45], v[160:161]
	v_pk_mul_f32 v[40:41], v[40:41], v[164:165]
	v_pk_mul_f32 v[36:37], v[36:37], v[168:169]
	v_pk_mul_f32 v[46:47], v[46:47], v[162:163]
	v_pk_mul_f32 v[42:43], v[42:43], v[166:167]
	v_pk_mul_f32 v[38:39], v[38:39], v[170:171]
	v_pk_mul_f32 v[34:35], v[34:35], v[174:175]
	v_pk_mul_f32 v[32:33], v[32:33], v[172:173]
	v_pk_mul_f32 v[28:29], v[28:29], v[160:161]
	v_pk_mul_f32 v[24:25], v[24:25], v[164:165]
	v_pk_mul_f32 v[20:21], v[20:21], v[168:169]
	v_pk_mul_f32 v[30:31], v[30:31], v[162:163]
	v_pk_mul_f32 v[26:27], v[26:27], v[166:167]
	v_pk_mul_f32 v[22:23], v[22:23], v[170:171]
	v_pk_mul_f32 v[18:19], v[18:19], v[174:175]
	v_pk_mul_f32 v[16:17], v[16:17], v[172:173]
; __device__ __forceinline__ void finishSM(f32x16& p0, f32x16& p1, float alpha, float& l_reg, bf16x8& pa0, bf16x8& pa1, bf16x8& pa2, bf16x8& pa3) {
;     ...
;   for (int r = 0; r < 16; ++r) p1[r] = __builtin_amdgcn_exp2f(p1[r]);
;   float ps = 0;
; #pragma unroll
;   for (int r = 0; r < 16; ++r) ps += p0[r];
; #pragma unroll
;   for (int r = 0; r < 16; ++r) ps += p1[r];
;   { auto rr = __builtin_amdgcn_permlane32_swap(__float_as_uint(ps), __float_as_uint(ps), false, false);
;     ps = __uint_as_float(rr[0]) + __uint_as_float(rr[1]); }
;   l_reg = l_reg * alpha + ps;
;     ...
;   PK4(p0, 0, pa0); PK4(p0, 8, pa1); PK4(p1, 0, pa2); PK4(p1, 8, pa3);
; template <int DKR, int NQ>
; __device__ __forceinline__ void qkt(f32x16& p0, f32x16& p1, const char* Ks, const char* Krs, const char* Qrs, const bf16x8* qr, int r32, int hi, int lane) {
;   p0 = f32x16{}; p1 = f32x16{};
; #pragma unroll
;   for (int d0 = 0; d0 < 8; ++d0) { int cb = (d0 * 16 + hi * 8) * 2;
;     bf16x8 b0 = *reinterpret_cast<const bf16x8*>(Ks + KSWZ(r32, cb));
;     bf16x8 b1 = *reinterpret_cast<const bf16x8*>(Ks + KSWZ(32 + r32, cb));
;     bf16x8 qf;
;     if (d0 >= 8 - NQ) qf = *reinterpret_cast<const bf16x8*>(Qrs + (d0 - (8 - NQ) + 4) * 1024 + lane * 16); else qf = qr[d0];
;     p0 = __builtin_amdgcn_mfma_f32_32x32x16_bf16(b0, qf, p0, 0, 0, 0);
;     p1 = __builtin_amdgcn_mfma_f32_32x32x16_bf16(b1, qf, p1, 0, 0, 0); }
.LBB0_620:
	v_cndmask_b32_e64 v203, v204, v203, s[4:5]
	v_mul_f32_e32 v204, 0xbe0293ee, v203
	v_fmamk_f32 v80, v80, 0x3e0293ee, v204
	v_fmamk_f32 v81, v81, 0x3e0293ee, v204
	v_fmamk_f32 v82, v82, 0x3e0293ee, v204
	v_fmamk_f32 v83, v83, 0x3e0293ee, v204
	v_fmamk_f32 v84, v84, 0x3e0293ee, v204
	v_fmamk_f32 v85, v85, 0x3e0293ee, v204
	v_fmamk_f32 v86, v86, 0x3e0293ee, v204
	v_fmamk_f32 v87, v87, 0x3e0293ee, v204
	v_fmamk_f32 v88, v88, 0x3e0293ee, v204
	v_fmamk_f32 v89, v89, 0x3e0293ee, v204
	v_fmamk_f32 v90, v90, 0x3e0293ee, v204
	v_fmamk_f32 v91, v91, 0x3e0293ee, v204
	v_fmamk_f32 v92, v92, 0x3e0293ee, v204
	v_fmamk_f32 v93, v93, 0x3e0293ee, v204
	v_fmamk_f32 v94, v94, 0x3e0293ee, v204
	v_fmamk_f32 v95, v95, 0x3e0293ee, v204
	v_exp_f32_e32 v160, v80
	v_exp_f32_e32 v175, v81
	v_exp_f32_e32 v161, v82
	v_exp_f32_e32 v174, v83
	v_exp_f32_e32 v162, v84
	v_exp_f32_e32 v173, v85
	v_exp_f32_e32 v163, v86
	v_exp_f32_e32 v172, v87
	v_exp_f32_e32 v164, v88
	v_exp_f32_e32 v171, v89
	v_exp_f32_e32 v165, v90
	v_exp_f32_e32 v170, v91
	v_exp_f32_e32 v166, v92
	v_exp_f32_e32 v169, v93
	v_exp_f32_e32 v167, v94
	v_exp_f32_e32 v168, v95
	v_fmamk_f32 v209, v69, 0x3e0293ee, v204
	v_fmamk_f32 v208, v76, 0x3e0293ee, v204
	v_fmamk_f32 v217, v64, 0x3e0293ee, v204
	v_fmamk_f32 v218, v65, 0x3e0293ee, v204
	v_fmamk_f32 v219, v66, 0x3e0293ee, v204
	v_fmamk_f32 v220, v67, 0x3e0293ee, v204
	v_fmamk_f32 v221, v68, 0x3e0293ee, v204
	v_fmamk_f32 v210, v70, 0x3e0293ee, v204
	v_fmamk_f32 v211, v71, 0x3e0293ee, v204
	v_fmamk_f32 v213, v72, 0x3e0293ee, v204
	v_fmamk_f32 v214, v73, 0x3e0293ee, v204
	v_fmamk_f32 v215, v74, 0x3e0293ee, v204
	v_fmamk_f32 v216, v75, 0x3e0293ee, v204
	v_fmamk_f32 v222, v77, 0x3e0293ee, v204
	v_fmamk_f32 v223, v78, 0x3e0293ee, v204
	v_fmac_f32_e32 v204, 0x3e0293ee, v79
	s_waitcnt lgkmcnt(0)
	s_barrier
	ds_read_b128 v[64:67], v194 offset:32768
	ds_read_b128 v[68:71], v194 offset:40960
	ds_read_b128 v[224:227], v200 offset:32768
	ds_read_b128 v[228:231], v200 offset:40960
	ds_read_b128 v[232:235], v201 offset:32768
	ds_read_b128 v[236:239], v201 offset:40960
	ds_read_b128 v[248:251], v195 offset:32768
	ds_read_b128 v[252:255], v195 offset:40960
	v_exp_f32_e32 v217, v217
	v_exp_f32_e32 v218, v218
	s_waitcnt lgkmcnt(7)
	v_mfma_f32_32x32x16_bf16 v[80:95], v[64:67], v[124:127], 0
	v_exp_f32_e32 v219, v219
	v_exp_f32_e32 v220, v220
	v_exp_f32_e32 v221, v221
	v_exp_f32_e32 v210, v210
	v_exp_f32_e32 v211, v211
	v_exp_f32_e32 v213, v213
	v_exp_f32_e32 v214, v214
	s_waitcnt lgkmcnt(6)
	v_mfma_f32_32x32x16_bf16 v[64:79], v[68:71], v[124:127], 0
	v_exp_f32_e32 v215, v215
	v_exp_f32_e32 v216, v216
	v_exp_f32_e32 v222, v222
	v_exp_f32_e32 v223, v223
	v_exp_f32_e32 v204, v204
	s_waitcnt lgkmcnt(5)
	v_mfma_f32_32x32x16_bf16 v[80:95], v[224:227], v[120:123], v[80:95]
	ds_read_b128 v[224:227], v196 offset:32768
	s_waitcnt lgkmcnt(5)
	v_mfma_f32_32x32x16_bf16 v[64:79], v[228:231], v[120:123], v[64:79]
	ds_read_b128 v[228:231], v196 offset:40960
	s_waitcnt lgkmcnt(5)
	v_mfma_f32_32x32x16_bf16 v[80:95], v[232:235], v[116:119], v[80:95]
	ds_read_b128 v[232:235], v197 offset:32768
	s_waitcnt lgkmcnt(5)
	v_mfma_f32_32x32x16_bf16 v[64:79], v[236:239], v[116:119], v[64:79]
	ds_read_b128 v[236:239], v197 offset:40960
	s_waitcnt lgkmcnt(5)
	v_mfma_f32_32x32x16_bf16 v[80:95], v[248:251], v[112:115], v[80:95]
	ds_read_b128 v[248:251], v198 offset:32768
	s_waitcnt lgkmcnt(5)
	v_mfma_f32_32x32x16_bf16 v[64:79], v[252:255], v[112:115], v[64:79]
	ds_read_b128 v[252:255], v198 offset:40960
	s_waitcnt lgkmcnt(5)
	v_mfma_f32_32x32x16_bf16 v[80:95], v[224:227], v[108:111], v[80:95]
	ds_read_b128 v[224:227], v199 offset:32768
	s_waitcnt lgkmcnt(5)
	v_mfma_f32_32x32x16_bf16 v[64:79], v[228:231], v[108:111], v[64:79]
	ds_read_b128 v[228:231], v199 offset:40960
	s_waitcnt lgkmcnt(5)
	v_mfma_f32_32x32x16_bf16 v[80:95], v[232:235], v[104:107], v[80:95]
	s_waitcnt lgkmcnt(4)
	v_mfma_f32_32x32x16_bf16 v[64:79], v[236:239], v[104:107], v[64:79]
	s_waitcnt lgkmcnt(3)
	v_mfma_f32_32x32x16_bf16 v[80:95], v[248:251], v[100:103], v[80:95]
	s_waitcnt lgkmcnt(2)
	v_mfma_f32_32x32x16_bf16 v[64:79], v[252:255], v[100:103], v[64:79]
	s_waitcnt lgkmcnt(1)
	v_mfma_f32_32x32x16_bf16 v[80:95], v[224:227], v[96:99], v[80:95]
	v_exp_f32_e32 v225, v208
	v_add_f32_e32 v208, 0, v160
	v_add_f32_e32 v208, v175, v208
	v_add_f32_e32 v208, v161, v208
	v_add_f32_e32 v208, v174, v208
	v_add_f32_e32 v208, v162, v208
	v_add_f32_e32 v208, v173, v208
	v_add_f32_e32 v208, v163, v208
	v_add_f32_e32 v208, v172, v208
	v_add_f32_e32 v208, v164, v208
	v_add_f32_e32 v208, v171, v208
	v_add_f32_e32 v208, v165, v208
	v_add_f32_e32 v208, v170, v208
	v_add_f32_e32 v208, v166, v208
	v_add_f32_e32 v208, v169, v208
	v_add_f32_e32 v208, v167, v208
	v_add_f32_e32 v208, v168, v208
	v_add_f32_e32 v208, v217, v208
	v_exp_f32_e32 v224, v209
	v_add_f32_e32 v208, v218, v208
	v_add_f32_e32 v208, v219, v208
	v_add_f32_e32 v208, v220, v208
	v_add_f32_e32 v208, v221, v208
	v_add_f32_e32 v208, v224, v208
	v_add_f32_e32 v208, v210, v208
	v_add_f32_e32 v208, v211, v208
	v_add_f32_e32 v208, v213, v208
	v_add_f32_e32 v208, v214, v208
	s_waitcnt lgkmcnt(0)
	v_mfma_f32_32x32x16_bf16 v[64:79], v[228:231], v[96:99], v[64:79]
	v_add_f32_e32 v208, v215, v208
	v_add_f32_e32 v208, v216, v208
	v_add_f32_e32 v208, v225, v208
	v_add_f32_e32 v208, v222, v208
	v_add_f32_e32 v208, v223, v208
	v_add_f32_e32 v208, v204, v208
	v_mov_b32_e32 v209, v208
	v_cvt_pk_bf16_f32 v160, v160, v175
	v_cvt_pk_bf16_f32 v161, v161, v174
	v_cvt_pk_bf16_f32 v162, v162, v173
	v_cvt_pk_bf16_f32 v163, v163, v172
	v_cvt_pk_bf16_f32 v164, v164, v171
	v_cvt_pk_bf16_f32 v165, v165, v170
	v_cvt_pk_bf16_f32 v166, v166, v169
	v_cvt_pk_bf16_f32 v167, v167, v168
	v_cvt_pk_bf16_f32 v168, v217, v218
	v_cvt_pk_bf16_f32 v169, v219, v220
	v_cvt_pk_bf16_f32 v170, v221, v224
	v_cvt_pk_bf16_f32 v171, v210, v211
	v_cvt_pk_bf16_f32 v172, v213, v214
	v_cvt_pk_bf16_f32 v173, v215, v216
	v_cvt_pk_bf16_f32 v174, v225, v222
	v_cvt_pk_bf16_f32 v175, v223, v204
	s_nop 1
	v_permlane32_swap_b32_e32 v208, v209
	v_permlane32_swap_b32_e32 v160, v162
	v_permlane32_swap_b32_e32 v161, v163
	v_permlane32_swap_b32_e32 v164, v166
	v_permlane32_swap_b32_e32 v165, v167
	v_permlane32_swap_b32_e32 v168, v170
	v_permlane32_swap_b32_e32 v169, v171
	v_permlane32_swap_b32_e32 v172, v174
	v_permlane32_swap_b32_e32 v173, v175
	s_cmp_gt_u32 s83, 32
	s_cselect_b64 s[14:15], -1, 0
	s_and_b64 vcc, exec, s[14:15]
	s_cbranch_vccnz .LBB0_622
	v_add_co_u32_e32 v128, vcc, 0xffffc000, v180
	s_nop 1
	v_addc_co_u32_e32 v129, vcc, -1, v181, vcc
	v_add_co_u32_e32 v130, vcc, 0xff6fc000, v180
	s_nop 1
	v_addc_co_u32_e32 v131, vcc, -1, v181, vcc
	v_add_co_u32_e32 v136, vcc, 0xff700000, v180
	global_load_dwordx4 v[132:135], v[128:129], off
	s_nop 0
	global_load_dwordx4 v[128:131], v[130:131], off
	v_addc_co_u32_e32 v137, vcc, -1, v181, vcc
	global_load_dwordx4 v[140:143], v[180:181], off
	s_nop 0
	global_load_dwordx4 v[136:139], v[136:137], off

; __device__ __forceinline__ unsigned xb_add(unsigned* p, unsigned v) { return __hip_atomic_fetch_add(p, v, __ATOMIC_RELAXED, __HIP_MEMORY_SCOPE_AGENT); }
; __device__ __forceinline__ void xcd_barrier(const XcdBarrier& b) {
;     ...
;             __builtin_amdgcn_fence(__ATOMIC_ACQUIRE, "agent");
;             xb_add(&bar[XB_XGEN(b.x)], 1u);
.LBB0_761:
	s_or_b64 exec, exec, s[0:1]
	s_mov_b64 s[0:1], exec
	v_mbcnt_lo_u32_b32 v0, s0, 0
	v_mbcnt_hi_u32_b32 v0, s1, v0
	v_cmp_eq_u32_e32 vcc, 0, v0
	s_waitcnt vmcnt(0)
	s_and_saveexec_b64 s[8:9], vcc
	s_cbranch_execz .LBB0_763
	s_bcnt1_i32_b64 s0, s[0:1]
	v_mov_b32_e32 v0, 0x2000
	v_mov_b32_e32 v1, s0
	global_atomic_add v0, v1, s[6:7] offset:1024

; __device__ __forceinline__ unsigned xb_add(unsigned* p, unsigned v) { return __hip_atomic_fetch_add(p, v, __ATOMIC_RELAXED, __HIP_MEMORY_SCOPE_AGENT); }
; __device__ __forceinline__ void xcd_barrier(const XcdBarrier& b) {
;     ...
;             __builtin_amdgcn_fence(__ATOMIC_ACQUIRE, "agent");
;             xb_add(&bar[XB_XGEN(b.x)], 1u);
.LBB0_1157:
	s_or_b64 exec, exec, s[4:5]
	s_mov_b64 s[4:5], exec
	v_mbcnt_lo_u32_b32 v0, s4, 0
	v_mbcnt_hi_u32_b32 v0, s5, v0
	v_cmp_eq_u32_e32 vcc, 0, v0
	s_waitcnt vmcnt(0)
	s_and_saveexec_b64 s[6:7], vcc
	s_cbranch_execz .LBB0_1159
	s_bcnt1_i32_b64 s4, s[4:5]
	v_mov_b32_e32 v0, 0x2000
	v_mov_b32_e32 v1, s4
	global_atomic_add v0, v1, s[0:1] offset:1024

; __global__ void __launch_bounds__(NTHR, 2) fwd_megakernel(Args A) {
	.amdhsa_kernel _Z14fwd_megakernel4Args
		.amdhsa_group_segment_fixed_size 0
		.amdhsa_private_segment_fixed_size 0
		.amdhsa_kernarg_size 456
		.amdhsa_user_sgpr_count 2
		.amdhsa_user_sgpr_dispatch_ptr 0
		.amdhsa_user_sgpr_queue_ptr 0
		.amdhsa_user_sgpr_kernarg_segment_ptr 1
		.amdhsa_user_sgpr_dispatch_id 0
		.amdhsa_user_sgpr_kernarg_preload_length 0
		.amdhsa_user_sgpr_kernarg_preload_offset 0
		.amdhsa_user_sgpr_private_segment_size 0
		.amdhsa_uses_dynamic_stack 0
		.amdhsa_enable_private_segment 0
		.amdhsa_system_sgpr_workgroup_id_x 1
		.amdhsa_system_sgpr_workgroup_id_y 0
		.amdhsa_system_sgpr_workgroup_id_z 0
		.amdhsa_system_sgpr_workgroup_info 0
		.amdhsa_system_vgpr_workitem_id 2
		.amdhsa_next_free_vgpr 256
		.amdhsa_next_free_sgpr 98
		.amdhsa_accum_offset 256
		.amdhsa_reserve_vcc 1
		.amdhsa_float_round_mode_32 0
		.amdhsa_float_round_mode_16_64 0
		.amdhsa_float_denorm_mode_32 3
		.amdhsa_float_denorm_mode_16_64 3
		.amdhsa_dx10_clamp 1
		.amdhsa_ieee_mode 1
		.amdhsa_fp16_overflow 0
		.amdhsa_tg_split 0
		.amdhsa_exception_fp_ieee_invalid_op 0
		.amdhsa_exception_fp_denorm_src 0
		.amdhsa_exception_fp_ieee_div_zero 0
		.amdhsa_exception_fp_ieee_overflow 0
		.amdhsa_exception_fp_ieee_underflow 0
		.amdhsa_exception_fp_ieee_inexact 0
		.amdhsa_exception_int_div_zero 0
	.end_amdhsa_kernel

; __global__ void __launch_bounds__(NTHR, 2) fwd_megakernel(Args A) {
amdhsa.kernels:
  - .agpr_count:     0
    .args:
      - .offset:         0
        .size:           200
        .value_kind:     by_value
      - .offset:         200
        .size:           4
        .value_kind:     hidden_block_count_x
      - .offset:         204
        .size:           4
        .value_kind:     hidden_block_count_y
      - .offset:         208
        .size:           4
        .value_kind:     hidden_block_count_z
      - .offset:         212
        .size:           2
        .value_kind:     hidden_group_size_x
      - .offset:         214
        .size:           2
        .value_kind:     hidden_group_size_y
      - .offset:         216
        .size:           2
        .value_kind:     hidden_group_size_z
      - .offset:         218
        .size:           2
        .value_kind:     hidden_remainder_x
      - .offset:         220
        .size:           2
        .value_kind:     hidden_remainder_y
      - .offset:         222
        .size:           2
        .value_kind:     hidden_remainder_z
      - .offset:         240
        .size:           8
        .value_kind:     hidden_global_offset_x
      - .offset:         248
        .size:           8
        .value_kind:     hidden_global_offset_y
      - .offset:         256
        .size:           8
        .value_kind:     hidden_global_offset_z
      - .offset:         264
        .size:           2
        .value_kind:     hidden_grid_dims
      - .offset:         288
        .size:           8
        .value_kind:     hidden_multigrid_sync_arg
      - .offset:         320
        .size:           4
        .value_kind:     hidden_dynamic_lds_size
    .group_segment_fixed_size: 0
    .kernarg_segment_align: 8
    .kernarg_segment_size: 456
    .language:       OpenCL C
    .language_version:
      - 2
      - 0
    .max_flat_workgroup_size: 512
    .name:           _Z14fwd_megakernel4Args
    .private_segment_fixed_size: 0
    .sgpr_count:     104
    .sgpr_spill_count: 46
    .symbol:         _Z14fwd_megakernel4Args.kd
    .uniform_work_group_size: 1
    .uses_dynamic_stack: false
    .vgpr_count:     256
    .vgpr_spill_count: 0
    .wavefront_size: 64
